# fox kv loop: split v_pk_fma/mul/add_f32 into scalar pairs (doc 7.5 packed-op anti-lever), bit-identical
# baseline (speedup 1.0000x reference)
.LBB0_331:
	s_cmp_gt_i32 s10, s7
	s_cselect_b64 s[0:1], -1, 0
	s_cmp_lt_i32 s2, s6
	s_cselect_b64 s[22:23], -1, 0
	s_or_b64 s[0:1], s[0:1], s[22:23]
	s_and_b64 vcc, exec, s[0:1]
	s_cbranch_vccnz .LBB0_337
	ds_read_b128 v[32:35], v146
	ds_read_b128 v[96:99], v146 offset:32
	s_cmp_eq_u32 s3, 0
	s_cselect_b64 s[0:1], -1, 0
	s_add_i32 s3, s10, 63
	s_waitcnt lgkmcnt(1)
	v_mfma_f32_32x32x16_bf16 v[48:63], v[32:35], v[64:67], 0
	ds_read_b128 v[32:35], v146 offset:4608
	s_cmp_gt_i32 s3, s52
	s_cselect_b64 s[22:23], -1, 0
	s_or_b64 s[22:23], s[0:1], s[22:23]
	s_mov_b64 s[0:1], -1
	s_and_b64 vcc, exec, s[22:23]
	s_waitcnt lgkmcnt(1)
	v_mfma_f32_32x32x16_bf16 v[48:63], v[96:99], v[68:71], v[48:63]
	ds_read_b128 v[96:99], v146 offset:4640
	s_waitcnt lgkmcnt(1)
	v_mfma_f32_32x32x16_bf16 v[32:47], v[32:35], v[64:67], 0
	s_waitcnt lgkmcnt(0)
	v_mfma_f32_32x32x16_bf16 v[32:47], v[96:99], v[68:71], v[32:47]
	ds_read_b128 v[96:99], v146 offset:64
	s_waitcnt lgkmcnt(0)
	v_mfma_f32_32x32x16_bf16 v[48:63], v[96:99], v[72:75], v[48:63]
	ds_read_b128 v[96:99], v146 offset:4672
	s_waitcnt lgkmcnt(0)
	v_mfma_f32_32x32x16_bf16 v[32:47], v[96:99], v[72:75], v[32:47]
	ds_read_b128 v[96:99], v146 offset:96
	s_waitcnt lgkmcnt(0)
	v_mfma_f32_32x32x16_bf16 v[48:63], v[96:99], v[76:79], v[48:63]
	ds_read_b128 v[96:99], v146 offset:4704
	s_waitcnt lgkmcnt(0)
	v_mfma_f32_32x32x16_bf16 v[32:47], v[96:99], v[76:79], v[32:47]
	s_cbranch_vccnz .LBB0_334
	ds_read_b128 v[96:99], v144 offset:18432
	ds_read_b128 v[118:121], v144 offset:18560
	ds_read_b128 v[124:127], v144 offset:18464
	ds_read_b128 v[128:131], v144 offset:18592
	ds_read_b128 v[132:135], v144 offset:18624
	ds_read_b128 v[152:155], v144 offset:18656
	s_waitcnt lgkmcnt(5)
	s_nop 0
	v_fma_f32 v114, v48, s42, v96
	v_fma_f32 v115, v49, s42, v97
	s_waitcnt lgkmcnt(4)
	s_nop 0
	v_fma_f32 v118, v32, s42, v118
	v_fma_f32 v119, v33, s42, v119
	v_fma_f32 v116, v50, s42, v98
	v_fma_f32 v117, v51, s42, v99
	v_max_f32_e32 v96, v114, v118
	v_max_f32_e32 v97, v115, v119
	v_fma_f32 v120, v34, s42, v120
	v_fma_f32 v121, v35, s42, v121
	v_max3_f32 v96, v96, s39, v97
	v_max_f32_e32 v97, v116, v120
	v_max_f32_e32 v98, v117, v121
	s_waitcnt lgkmcnt(3)
	v_fma_f32 v122, v52, s42, v124
	v_fma_f32 v123, v53, s42, v125
	s_waitcnt lgkmcnt(2)
	v_fma_f32 v124, v36, s42, v128
	v_fma_f32 v125, v37, s42, v129
	v_max3_f32 v96, v96, v97, v98
	v_max_f32_e32 v97, v122, v124
	v_max_f32_e32 v98, v123, v125
	v_max3_f32 v136, v96, v97, v98
	ds_read_b128 v[96:99], v144 offset:18496
	v_fma_f32 v126, v54, s42, v126
	v_fma_f32 v127, v55, s42, v127
	v_fma_f32 v128, v38, s42, v130
	v_fma_f32 v129, v39, s42, v131
	s_mov_b64 s[0:1], 0
	v_max_f32_e32 v130, v126, v128
	v_max_f32_e32 v131, v127, v129
	v_max3_f32 v140, v136, v130, v131
	ds_read_b128 v[136:139], v144 offset:18528
	s_waitcnt lgkmcnt(1)
	v_fma_f32 v130, v56, s42, v96
	v_fma_f32 v131, v57, s42, v97
	v_fma_f32 v96, v40, s42, v132
	v_fma_f32 v97, v41, s42, v133
	s_waitcnt lgkmcnt(0)
	v_fma_f32 v138, v62, s42, v138
	v_fma_f32 v139, v63, s42, v139
	v_max_f32_e32 v132, v130, v96
	v_max_f32_e32 v133, v131, v97
	v_max3_f32 v140, v140, v132, v133
	v_fma_f32 v132, v58, s42, v98
	v_fma_f32 v133, v59, s42, v99
	v_fma_f32 v98, v42, s42, v134
	v_fma_f32 v99, v43, s42, v135
	s_nop 0
	v_max_f32_e32 v134, v132, v98
	v_max_f32_e32 v135, v133, v99
	v_max3_f32 v156, v140, v134, v135
	v_fma_f32 v140, v60, s42, v136
	v_fma_f32 v141, v61, s42, v137
	v_fma_f32 v134, v44, s42, v152
	v_fma_f32 v135, v45, s42, v153
	s_nop 0
	v_max_f32_e32 v136, v140, v134
	v_max_f32_e32 v137, v141, v135
	v_max3_f32 v152, v156, v136, v137
	v_fma_f32 v136, v46, s42, v154
	v_fma_f32 v137, v47, s42, v155
	s_nop 0
	v_max_f32_e32 v153, v138, v136
	v_max_f32_e32 v154, v139, v137
	v_max3_f32 v152, v152, v153, v154

.LBB0_336:
	s_nop 8
	ds_bpermute_b32 v32, v103, v152
	s_waitcnt lgkmcnt(0)
	v_max3_f32 v33, v151, v152, v32
	v_sub_f32_e32 v34, v114, v33
	v_exp_f32_e32 v52, v34
	v_sub_f32_e32 v34, v119, v33
	v_sub_f32_e32 v36, v115, v33
	v_exp_f32_e32 v115, v34
	v_sub_f32_e32 v34, v116, v33
	v_exp_f32_e32 v54, v34
	v_sub_f32_e32 v34, v120, v33
	v_exp_f32_e32 v116, v34
	v_sub_f32_e32 v34, v117, v33
	v_exp_f32_e32 v117, v34
	v_sub_f32_e32 v34, v121, v33
	v_exp_f32_e32 v121, v34
	v_sub_f32_e32 v34, v122, v33
	v_sub_f32_e32 v48, v138, v33
	v_add_u32_e32 v122, 0x2000, v149
	v_exp_f32_e32 v61, v48
	ds_read2_b64 v[48:51], v122 offset0:128 offset1:130
	v_sub_f32_e32 v32, v151, v33
	v_sub_f32_e32 v35, v118, v33
	v_exp_f32_e32 v32, v32
	v_exp_f32_e32 v114, v35
	v_exp_f32_e32 v53, v36
	v_exp_f32_e32 v35, v34
	v_sub_f32_e32 v34, v124, v33
	v_sub_f32_e32 v38, v126, v33
	v_exp_f32_e32 v37, v34
	v_sub_f32_e32 v34, v123, v33
	v_exp_f32_e32 v39, v38
	v_sub_f32_e32 v38, v128, v33
	v_add_u32_e32 v123, 0x3000, v149
	v_exp_f32_e32 v41, v38
	v_sub_f32_e32 v38, v127, v33
	v_mul_f32_e32 v30, v30, v32
	v_mul_f32_e32 v31, v31, v32
	v_mul_f32_e32 v28, v28, v32
	v_mul_f32_e32 v29, v29, v32
	v_mul_f32_e32 v26, v26, v32
	v_mul_f32_e32 v27, v27, v32
	v_mul_f32_e32 v24, v24, v32
	v_mul_f32_e32 v25, v25, v32
	v_mul_f32_e32 v22, v22, v32
	v_mul_f32_e32 v23, v23, v32
	v_mul_f32_e32 v20, v20, v32
	v_mul_f32_e32 v21, v21, v32
	v_mul_f32_e32 v18, v18, v32
	v_mul_f32_e32 v19, v19, v32
	v_mul_f32_e32 v16, v16, v32
	v_mul_f32_e32 v17, v17, v32
	ds_read2_b64 v[56:59], v123 offset0:192 offset1:194
	v_add_f32_e32 v118, v52, v114
	v_add_f32_e32 v119, v53, v115
	v_add_f32_e32 v120, v54, v116
	v_exp_f32_e32 v34, v34
	v_exp_f32_e32 v38, v38
	v_cvt_pk_bf16_f32 v52, v52, v53
	v_cvt_pk_bf16_f32 v53, v54, v117
	v_cvt_pk_bf16_f32 v54, v35, v34
	v_cvt_pk_bf16_f32 v55, v39, v38
	v_sub_f32_e32 v42, v130, v33
	s_waitcnt lgkmcnt(1)
	v_mfma_f32_32x32x16_bf16 v[16:31], v[48:51], v[52:55], v[16:31]
	ds_read2_b64 v[48:51], v122 offset0:132 offset1:134
	v_sub_f32_e32 v44, v132, v33
	v_sub_f32_e32 v46, v140, v33
	v_mul_f32_e64 v14, v14, v32
	v_mul_f32_e64 v15, v15, v32
	v_mul_f32_e32 v12, v12, v32
	v_mul_f32_e32 v13, v13, v32
	v_mul_f32_e32 v10, v10, v32
	v_mul_f32_e32 v11, v11, v32
	v_mul_f32_e32 v8, v8, v32
	v_mul_f32_e32 v9, v9, v32
	v_mul_f32_e32 v6, v6, v32
	v_mul_f32_e32 v7, v7, v32
	v_mul_f32_e32 v4, v4, v32
	v_mul_f32_e32 v5, v5, v32
	v_mul_f32_e32 v2, v2, v32
	v_mul_f32_e32 v3, v3, v32
	v_mul_f32_e32 v0, v0, v32
	v_mul_f32_e32 v1, v1, v32
	v_exp_f32_e32 v43, v42
	v_sub_f32_e32 v42, v131, v33
	v_exp_f32_e32 v45, v44
	v_sub_f32_e32 v44, v133, v33
	v_exp_f32_e32 v47, v46
	v_sub_f32_e32 v46, v141, v33
	s_waitcnt lgkmcnt(1)
	v_mfma_f32_32x32x16_bf16 v[0:15], v[56:59], v[52:55], v[0:15]
	v_sub_f32_e32 v52, v139, v33
	v_exp_f32_e32 v42, v42
	v_exp_f32_e32 v44, v44
	v_exp_f32_e32 v46, v46
	v_exp_f32_e32 v60, v52
	v_cvt_pk_bf16_f32 v52, v43, v42
	v_cvt_pk_bf16_f32 v53, v45, v44
	v_cvt_pk_bf16_f32 v54, v47, v46
	v_cvt_pk_bf16_f32 v55, v61, v60
	ds_read2_b64 v[56:59], v123 offset0:196 offset1:198
	s_waitcnt lgkmcnt(1)
	v_mfma_f32_32x32x16_bf16 v[16:31], v[48:51], v[52:55], v[16:31]
	v_sub_f32_e32 v48, v96, v33
	v_exp_f32_e32 v63, v48
	v_sub_f32_e32 v48, v97, v33
	v_exp_f32_e32 v62, v48
	v_sub_f32_e32 v48, v98, v33
	v_exp_f32_e32 v97, v48
	ds_read2_b64 v[48:51], v122 offset0:136 offset1:138
	v_sub_f32_e32 v36, v125, v33
	v_sub_f32_e32 v40, v129, v33
	s_waitcnt lgkmcnt(1)
	v_mfma_f32_32x32x16_bf16 v[0:15], v[56:59], v[52:55], v[0:15]
	v_sub_f32_e32 v52, v99, v33
	v_exp_f32_e32 v36, v36
	v_exp_f32_e32 v40, v40
	v_exp_f32_e32 v96, v52
	v_cvt_pk_bf16_f32 v52, v114, v115
	v_cvt_pk_bf16_f32 v53, v116, v121
	v_cvt_pk_bf16_f32 v54, v37, v36
	v_cvt_pk_bf16_f32 v55, v41, v40
	ds_read2_b64 v[56:59], v123 offset0:200 offset1:202
	s_waitcnt lgkmcnt(1)
	v_mfma_f32_32x32x16_bf16 v[16:31], v[48:51], v[52:55], v[16:31]
	v_sub_f32_e32 v48, v134, v33
	v_exp_f32_e32 v99, v48
	v_sub_f32_e32 v48, v135, v33
	v_exp_f32_e32 v98, v48
	v_sub_f32_e32 v48, v136, v33
	v_exp_f32_e32 v115, v48
	ds_read2_b64 v[48:51], v122 offset0:140 offset1:142
	v_add_f32_e32 v34, v34, v36
	v_add_f32_e32 v35, v35, v37
	v_add_f32_e32 v36, v38, v40
	v_add_f32_e32 v37, v39, v41
	v_add_f32_e32 v38, v42, v62
	v_add_f32_e32 v39, v43, v63
	v_add_f32_e32 v42, v46, v98
	v_add_f32_e32 v43, v47, v99
	v_add_f32_e32 v46, 0, v118
	s_waitcnt lgkmcnt(1)
	v_mfma_f32_32x32x16_bf16 v[0:15], v[56:59], v[52:55], v[0:15]
	v_sub_f32_e32 v52, v137, v33
	ds_read2_b64 v[56:59], v123 offset0:204 offset1:206
	v_add_f32_e32 v46, v119, v46
	v_exp_f32_e32 v114, v52
	v_cvt_pk_bf16_f32 v52, v63, v62
	v_cvt_pk_bf16_f32 v53, v97, v96
	v_cvt_pk_bf16_f32 v54, v99, v98
	v_cvt_pk_bf16_f32 v55, v115, v114
	v_add_f32_e32 v46, v120, v46
	s_waitcnt lgkmcnt(1)
	v_mfma_f32_32x32x16_bf16 v[16:31], v[48:51], v[52:55], v[16:31]
	v_add_f32_e32 v48, v117, v121
	v_add_f32_e32 v46, v48, v46
	v_add_f32_e32 v35, v35, v46
	v_add_f32_e32 v34, v34, v35
	v_add_f32_e32 v34, v37, v34
	v_add_f32_e32 v34, v36, v34
	v_add_f32_e32 v34, v39, v34
	v_add_f32_e32 v40, v44, v96
	v_add_f32_e32 v41, v45, v97
	v_add_f32_e32 v34, v38, v34
	s_waitcnt lgkmcnt(0)
	v_mfma_f32_32x32x16_bf16 v[0:15], v[56:59], v[52:55], v[0:15]
	v_add_f32_e32 v34, v41, v34
	v_add_f32_e32 v34, v40, v34
	v_add_f32_e32 v34, v43, v34
	v_add_f32_e64 v44, v60, v114
	v_add_f32_e64 v45, v61, v115
	v_add_f32_e32 v34, v42, v34
	v_add_f32_e32 v34, v45, v34
	v_add_f32_e32 v34, v44, v34
	v_fmac_f32_e32 v34, v109, v32
	v_mov_b32_e32 v151, v33
	v_mov_b32_e32 v109, v34
